# barrier polling loops without s_sleep (tighter spin) on top of v34
# speedup vs baseline: 1.0027x; 1.0027x over previous
.LBB0_12:
	s_nop 0
	global_load_dword v3, v2, s[6:7] offset:32 sc1
	s_waitcnt vmcnt(0)
	v_and_b32_e32 v3, 0xffff0000, v3
	v_cmp_ne_u32_e32 vcc, v3, v1
	s_or_b64 s[8:9], vcc, s[8:9]
	s_andn2_b64 exec, exec, s[8:9]
	s_cbranch_execnz .LBB0_12

.LBB0_27:
	global_load_dword v15, v16, s[6:7] sc1
	s_waitcnt lgkmcnt(0)
	global_load_dword v0, v16, s[8:9] sc1
	global_load_dword v1, v16, s[10:11] sc1
	global_load_dword v2, v16, s[14:15] sc1
	global_load_dword v3, v16, s[34:35] sc1
	global_load_dword v4, v16, s[36:37] sc1
	global_load_dword v5, v16, s[38:39] sc1
	global_load_dword v6, v16, s[40:41] sc1
	global_load_dword v7, v16, s[42:43] sc1
	global_load_dword v8, v16, s[44:45] sc1
	global_load_dword v9, v16, s[46:47] sc1
	global_load_dword v10, v16, s[48:49] sc1
	global_load_dword v11, v16, s[50:51] sc1
	global_load_dword v12, v16, s[88:89] sc1
	global_load_dword v13, v16, s[90:91] sc1
	global_load_dword v14, v16, s[92:93] sc1
	s_mov_b64 s[94:95], -1
	s_mov_b64 s[78:79], -1
	s_waitcnt vmcnt(14)
	v_add_u32_e32 v17, v0, v15
	s_waitcnt vmcnt(13)
	v_add_u32_e32 v17, v17, v1
	s_waitcnt vmcnt(12)
	v_add_u32_e32 v17, v17, v2
	s_waitcnt vmcnt(11)
	v_add_u32_e32 v17, v17, v3
	s_waitcnt vmcnt(10)
	v_add_u32_e32 v17, v17, v4
	s_waitcnt vmcnt(9)
	v_add_u32_e32 v17, v17, v5
	s_waitcnt vmcnt(8)
	v_add_u32_e32 v17, v17, v6
	s_waitcnt vmcnt(7)
	v_add_u32_e32 v17, v17, v7
	s_waitcnt vmcnt(6)
	v_add_u32_e32 v17, v17, v8
	s_waitcnt vmcnt(5)
	v_add_u32_e32 v17, v17, v9
	s_waitcnt vmcnt(4)
	v_add_u32_e32 v17, v17, v10
	s_waitcnt vmcnt(3)
	v_add_u32_e32 v17, v17, v11
	s_waitcnt vmcnt(2)
	v_add_u32_e32 v17, v17, v12
	s_waitcnt vmcnt(1)
	v_add_u32_e32 v17, v17, v13
	s_waitcnt vmcnt(0)
	v_add_u32_e32 v17, v17, v14
	v_cmp_eq_u32_e32 vcc, s13, v17
	s_cbranch_vccnz .LBB0_26
	s_and_b32 s17, s16, 0xff
	s_cmp_eq_u32 s17, 0
	s_mov_b64 s[84:85], -1
	s_nop 0
	s_cbranch_scc0 .LBB0_31
	global_load_dword v17, v16, s[4:5] sc1
	s_waitcnt vmcnt(0)
	v_cmp_eq_u32_e32 vcc, 0, v17
	s_cbranch_vccnz .LBB0_33
	s_mov_b64 s[84:85], 0

.LBB0_45:
	s_and_b32 s16, s13, 0xff
	s_mov_b64 s[38:39], -1
	s_cmp_lg_u32 s16, 0
	s_mov_b64 s[42:43], -1
	s_nop 0
	s_cbranch_scc1 .LBB0_48
	global_load_dword v2, v0, s[10:11] sc1
	s_waitcnt vmcnt(0)
	v_cmp_eq_u32_e32 vcc, 0, v2
	s_cbranch_vccnz .LBB0_50
	s_mov_b64 s[42:43], 0
	s_mov_b64 s[40:41], -1

.LBB0_62:
	s_and_b32 s16, s13, 0xff
	s_cmp_lg_u32 s16, 0
	s_mov_b64 s[40:41], -1
	s_nop 0
	s_cbranch_scc1 .LBB0_65
	global_load_dword v1, v0, s[10:11] sc1
	s_waitcnt vmcnt(0)
	v_cmp_eq_u32_e32 vcc, 0, v1
	s_cbranch_vccnz .LBB0_67
	s_mov_b64 s[40:41], 0
	s_mov_b64 s[38:39], -1

.LBB0_150:
	global_load_dword v15, v16, s[4:5] sc1
	s_waitcnt lgkmcnt(0)
	global_load_dword v0, v16, s[8:9] sc1
	global_load_dword v1, v16, s[10:11] sc1
	global_load_dword v2, v16, s[14:15] sc1
	global_load_dword v3, v16, s[34:35] sc1
	global_load_dword v4, v16, s[36:37] sc1
	global_load_dword v5, v16, s[38:39] sc1
	global_load_dword v6, v16, s[40:41] sc1
	global_load_dword v7, v16, s[42:43] sc1
	global_load_dword v8, v16, s[44:45] sc1
	global_load_dword v9, v16, s[46:47] sc1
	global_load_dword v10, v16, s[48:49] sc1
	global_load_dword v11, v16, s[50:51] sc1
	global_load_dword v12, v16, s[58:59] sc1
	global_load_dword v13, v16, s[60:61] sc1
	global_load_dword v14, v16, s[62:63] sc1
	s_mov_b64 s[90:91], -1
	s_mov_b64 s[78:79], -1
	s_waitcnt vmcnt(14)
	v_add_u32_e32 v17, v0, v15
	s_waitcnt vmcnt(13)
	v_add_u32_e32 v17, v17, v1
	s_waitcnt vmcnt(12)
	v_add_u32_e32 v17, v17, v2
	s_waitcnt vmcnt(11)
	v_add_u32_e32 v17, v17, v3
	s_waitcnt vmcnt(10)
	v_add_u32_e32 v17, v17, v4
	s_waitcnt vmcnt(9)
	v_add_u32_e32 v17, v17, v5
	s_waitcnt vmcnt(8)
	v_add_u32_e32 v17, v17, v6
	s_waitcnt vmcnt(7)
	v_add_u32_e32 v17, v17, v7
	s_waitcnt vmcnt(6)
	v_add_u32_e32 v17, v17, v8
	s_waitcnt vmcnt(5)
	v_add_u32_e32 v17, v17, v9
	s_waitcnt vmcnt(4)
	v_add_u32_e32 v17, v17, v10
	s_waitcnt vmcnt(3)
	v_add_u32_e32 v17, v17, v11
	s_waitcnt vmcnt(2)
	v_add_u32_e32 v17, v17, v12
	s_waitcnt vmcnt(1)
	v_add_u32_e32 v17, v17, v13
	s_waitcnt vmcnt(0)
	v_add_u32_e32 v17, v17, v14
	v_cmp_eq_u32_e32 vcc, s13, v17
	s_cbranch_vccnz .LBB0_149
	s_and_b32 s17, s16, 0xff
	s_cmp_eq_u32 s17, 0
	s_mov_b64 s[84:85], -1
	s_nop 0
	s_cbranch_scc0 .LBB0_154
	global_load_dword v17, v16, s[2:3] sc1
	s_waitcnt vmcnt(0)
	v_cmp_eq_u32_e32 vcc, 0, v17
	s_cbranch_vccnz .LBB0_156
	s_mov_b64 s[84:85], 0

.LBB0_221:
	global_load_dword v15, v16, s[6:7] sc1
	s_waitcnt lgkmcnt(0)
	global_load_dword v0, v16, s[8:9] sc1
	global_load_dword v1, v16, s[10:11] sc1
	global_load_dword v2, v16, s[14:15] sc1
	global_load_dword v3, v16, s[34:35] sc1
	global_load_dword v4, v16, s[36:37] sc1
	global_load_dword v5, v16, s[38:39] sc1
	global_load_dword v6, v16, s[40:41] sc1
	global_load_dword v7, v16, s[42:43] sc1
	global_load_dword v8, v16, s[44:45] sc1
	global_load_dword v9, v16, s[46:47] sc1
	global_load_dword v10, v16, s[48:49] sc1
	global_load_dword v11, v16, s[50:51] sc1
	global_load_dword v12, v16, s[60:61] sc1
	global_load_dword v13, v16, s[62:63] sc1
	global_load_dword v14, v16, s[90:91] sc1
	s_mov_b64 s[92:93], -1
	s_mov_b64 s[78:79], -1
	s_waitcnt vmcnt(14)
	v_add_u32_e32 v17, v0, v15
	s_waitcnt vmcnt(13)
	v_add_u32_e32 v17, v17, v1
	s_waitcnt vmcnt(12)
	v_add_u32_e32 v17, v17, v2
	s_waitcnt vmcnt(11)
	v_add_u32_e32 v17, v17, v3
	s_waitcnt vmcnt(10)
	v_add_u32_e32 v17, v17, v4
	s_waitcnt vmcnt(9)
	v_add_u32_e32 v17, v17, v5
	s_waitcnt vmcnt(8)
	v_add_u32_e32 v17, v17, v6
	s_waitcnt vmcnt(7)
	v_add_u32_e32 v17, v17, v7
	s_waitcnt vmcnt(6)
	v_add_u32_e32 v17, v17, v8
	s_waitcnt vmcnt(5)
	v_add_u32_e32 v17, v17, v9
	s_waitcnt vmcnt(4)
	v_add_u32_e32 v17, v17, v10
	s_waitcnt vmcnt(3)
	v_add_u32_e32 v17, v17, v11
	s_waitcnt vmcnt(2)
	v_add_u32_e32 v17, v17, v12
	s_waitcnt vmcnt(1)
	v_add_u32_e32 v17, v17, v13
	s_waitcnt vmcnt(0)
	v_add_u32_e32 v17, v17, v14
	v_cmp_eq_u32_e32 vcc, s13, v17
	s_cbranch_vccnz .LBB0_220
	s_and_b32 s17, s16, 0xff
	s_cmp_eq_u32 s17, 0
	s_mov_b64 s[84:85], -1
	s_nop 0
	s_cbranch_scc0 .LBB0_225
	global_load_dword v17, v16, s[4:5] sc1
	s_waitcnt vmcnt(0)
	v_cmp_eq_u32_e32 vcc, 0, v17
	s_cbranch_vccnz .LBB0_227
	s_mov_b64 s[84:85], 0

.LBB0_292:
	global_load_dword v15, v16, s[4:5] sc1
	s_waitcnt lgkmcnt(0)
	global_load_dword v0, v16, s[6:7] sc1
	global_load_dword v1, v16, s[8:9] sc1
	global_load_dword v2, v16, s[14:15] sc1
	global_load_dword v3, v16, s[34:35] sc1
	global_load_dword v4, v16, s[36:37] sc1
	global_load_dword v5, v16, s[38:39] sc1
	global_load_dword v6, v16, s[40:41] sc1
	global_load_dword v7, v16, s[42:43] sc1
	global_load_dword v8, v16, s[44:45] sc1
	global_load_dword v9, v16, s[46:47] sc1
	global_load_dword v10, v16, s[48:49] sc1
	global_load_dword v11, v16, s[50:51] sc1
	global_load_dword v12, v16, s[62:63] sc1
	global_load_dword v13, v16, s[90:91] sc1
	global_load_dword v14, v16, s[92:93] sc1
	s_mov_b64 s[94:95], -1
	s_mov_b64 s[78:79], -1
	s_waitcnt vmcnt(14)
	v_add_u32_e32 v17, v0, v15
	s_waitcnt vmcnt(13)
	v_add_u32_e32 v17, v17, v1
	s_waitcnt vmcnt(12)
	v_add_u32_e32 v17, v17, v2
	s_waitcnt vmcnt(11)
	v_add_u32_e32 v17, v17, v3
	s_waitcnt vmcnt(10)
	v_add_u32_e32 v17, v17, v4
	s_waitcnt vmcnt(9)
	v_add_u32_e32 v17, v17, v5
	s_waitcnt vmcnt(8)
	v_add_u32_e32 v17, v17, v6
	s_waitcnt vmcnt(7)
	v_add_u32_e32 v17, v17, v7
	s_waitcnt vmcnt(6)
	v_add_u32_e32 v17, v17, v8
	s_waitcnt vmcnt(5)
	v_add_u32_e32 v17, v17, v9
	s_waitcnt vmcnt(4)
	v_add_u32_e32 v17, v17, v10
	s_waitcnt vmcnt(3)
	v_add_u32_e32 v17, v17, v11
	s_waitcnt vmcnt(2)
	v_add_u32_e32 v17, v17, v12
	s_waitcnt vmcnt(1)
	v_add_u32_e32 v17, v17, v13
	s_waitcnt vmcnt(0)
	v_add_u32_e32 v17, v17, v14
	v_cmp_eq_u32_e32 vcc, s13, v17
	s_cbranch_vccnz .LBB0_291
	s_and_b32 s17, s16, 0xff
	s_cmp_eq_u32 s17, 0
	s_mov_b64 s[84:85], -1
	s_nop 0
	s_cbranch_scc0 .LBB0_296
	global_load_dword v17, v16, s[2:3] sc1
	s_waitcnt vmcnt(0)
	v_cmp_eq_u32_e32 vcc, 0, v17
	s_cbranch_vccnz .LBB0_298
	s_mov_b64 s[84:85], 0

.LBB0_310:
	s_and_b32 s16, s13, 0xff
	s_mov_b64 s[38:39], -1
	s_cmp_lg_u32 s16, 0
	s_mov_b64 s[42:43], -1
	s_nop 0
	s_cbranch_scc1 .LBB0_313
	global_load_dword v2, v0, s[8:9] sc1
	s_waitcnt vmcnt(0)
	v_cmp_eq_u32_e32 vcc, 0, v2
	s_cbranch_vccnz .LBB0_315
	s_mov_b64 s[42:43], 0
	s_mov_b64 s[40:41], -1

.LBB0_327:
	s_and_b32 s16, s13, 0xff
	s_cmp_lg_u32 s16, 0
	s_mov_b64 s[40:41], -1
	s_nop 0
	s_cbranch_scc1 .LBB0_330
	global_load_dword v1, v0, s[8:9] sc1
	s_waitcnt vmcnt(0)
	v_cmp_eq_u32_e32 vcc, 0, v1
	s_cbranch_vccnz .LBB0_332
	s_mov_b64 s[40:41], 0
	s_mov_b64 s[38:39], -1

.LBB0_369:
	global_load_dword v15, v16, s[6:7] sc1
	s_waitcnt lgkmcnt(0)
	global_load_dword v0, v16, s[8:9] sc1
	global_load_dword v1, v16, s[10:11] sc1
	global_load_dword v2, v16, s[14:15] sc1
	global_load_dword v3, v16, s[34:35] sc1
	global_load_dword v4, v16, s[36:37] sc1
	global_load_dword v5, v16, s[38:39] sc1
	global_load_dword v6, v16, s[40:41] sc1
	global_load_dword v7, v16, s[42:43] sc1
	global_load_dword v8, v16, s[44:45] sc1
	global_load_dword v9, v16, s[46:47] sc1
	global_load_dword v10, v16, s[48:49] sc1
	global_load_dword v11, v16, s[50:51] sc1
	global_load_dword v12, v16, s[90:91] sc1
	global_load_dword v13, v16, s[92:93] sc1
	global_load_dword v14, v16, s[94:95] sc1
	s_mov_b64 s[96:97], -1
	s_mov_b64 s[78:79], -1
	s_waitcnt vmcnt(14)
	v_add_u32_e32 v17, v0, v15
	s_waitcnt vmcnt(13)
	v_add_u32_e32 v17, v17, v1
	s_waitcnt vmcnt(12)
	v_add_u32_e32 v17, v17, v2
	s_waitcnt vmcnt(11)
	v_add_u32_e32 v17, v17, v3
	s_waitcnt vmcnt(10)
	v_add_u32_e32 v17, v17, v4
	s_waitcnt vmcnt(9)
	v_add_u32_e32 v17, v17, v5
	s_waitcnt vmcnt(8)
	v_add_u32_e32 v17, v17, v6
	s_waitcnt vmcnt(7)
	v_add_u32_e32 v17, v17, v7
	s_waitcnt vmcnt(6)
	v_add_u32_e32 v17, v17, v8
	s_waitcnt vmcnt(5)
	v_add_u32_e32 v17, v17, v9
	s_waitcnt vmcnt(4)
	v_add_u32_e32 v17, v17, v10
	s_waitcnt vmcnt(3)
	v_add_u32_e32 v17, v17, v11
	s_waitcnt vmcnt(2)
	v_add_u32_e32 v17, v17, v12
	s_waitcnt vmcnt(1)
	v_add_u32_e32 v17, v17, v13
	s_waitcnt vmcnt(0)
	v_add_u32_e32 v17, v17, v14
	v_cmp_eq_u32_e32 vcc, s13, v17
	s_cbranch_vccnz .LBB0_368
	s_and_b32 s17, s16, 0xff
	s_cmp_eq_u32 s17, 0
	s_mov_b64 s[84:85], -1
	s_nop 0
	s_cbranch_scc0 .LBB0_373
	global_load_dword v17, v16, s[4:5] sc1
	s_waitcnt vmcnt(0)
	v_cmp_eq_u32_e32 vcc, 0, v17
	s_cbranch_vccnz .LBB0_375
	s_mov_b64 s[84:85], 0

.LBB0_446:
	global_load_dword v15, v16, s[4:5] sc1
	s_waitcnt lgkmcnt(0)
	global_load_dword v0, v16, s[6:7] sc1
	global_load_dword v1, v16, s[8:9] sc1
	global_load_dword v2, v16, s[10:11] sc1
	global_load_dword v3, v16, s[14:15] sc1
	global_load_dword v4, v16, s[34:35] sc1
	global_load_dword v5, v16, s[36:37] sc1
	global_load_dword v6, v16, s[38:39] sc1
	global_load_dword v7, v16, s[40:41] sc1
	global_load_dword v8, v16, s[42:43] sc1
	global_load_dword v9, v16, s[44:45] sc1
	global_load_dword v10, v16, s[46:47] sc1
	global_load_dword v11, v16, s[48:49] sc1
	global_load_dword v12, v16, s[50:51] sc1
	global_load_dword v13, v16, s[92:93] sc1
	global_load_dword v14, v16, s[94:95] sc1
	s_mov_b64 s[96:97], -1
	s_mov_b64 s[78:79], -1
	s_waitcnt vmcnt(14)
	v_add_u32_e32 v17, v0, v15
	s_waitcnt vmcnt(13)
	v_add_u32_e32 v17, v17, v1
	s_waitcnt vmcnt(12)
	v_add_u32_e32 v17, v17, v2
	s_waitcnt vmcnt(11)
	v_add_u32_e32 v17, v17, v3
	s_waitcnt vmcnt(10)
	v_add_u32_e32 v17, v17, v4
	s_waitcnt vmcnt(9)
	v_add_u32_e32 v17, v17, v5
	s_waitcnt vmcnt(8)
	v_add_u32_e32 v17, v17, v6
	s_waitcnt vmcnt(7)
	v_add_u32_e32 v17, v17, v7
	s_waitcnt vmcnt(6)
	v_add_u32_e32 v17, v17, v8
	s_waitcnt vmcnt(5)
	v_add_u32_e32 v17, v17, v9
	s_waitcnt vmcnt(4)
	v_add_u32_e32 v17, v17, v10
	s_waitcnt vmcnt(3)
	v_add_u32_e32 v17, v17, v11
	s_waitcnt vmcnt(2)
	v_add_u32_e32 v17, v17, v12
	s_waitcnt vmcnt(1)
	v_add_u32_e32 v17, v17, v13
	s_waitcnt vmcnt(0)
	v_add_u32_e32 v17, v17, v14
	v_cmp_eq_u32_e32 vcc, s13, v17
	s_cbranch_vccnz .LBB0_445
	s_and_b32 s17, s16, 0xff
	s_cmp_eq_u32 s17, 0
	s_mov_b64 s[84:85], -1
	s_nop 0
	s_cbranch_scc0 .LBB0_450
	global_load_dword v17, v16, s[2:3] sc1
	s_waitcnt vmcnt(0)
	v_cmp_eq_u32_e32 vcc, 0, v17
	s_cbranch_vccnz .LBB0_452
	s_mov_b64 s[84:85], 0

.LBB0_464:
	s_and_b32 s16, s13, 0xff
	s_mov_b64 s[36:37], -1
	s_cmp_lg_u32 s16, 0
	s_mov_b64 s[40:41], -1
	s_nop 0
	s_cbranch_scc1 .LBB0_467
	global_load_dword v2, v0, s[8:9] sc1
	s_waitcnt vmcnt(0)
	v_cmp_eq_u32_e32 vcc, 0, v2
	s_cbranch_vccnz .LBB0_469
	s_mov_b64 s[40:41], 0
	s_mov_b64 s[38:39], -1

.LBB0_481:
	s_and_b32 s16, s13, 0xff
	s_cmp_lg_u32 s16, 0
	s_mov_b64 s[38:39], -1
	s_nop 0
	s_cbranch_scc1 .LBB0_484
	global_load_dword v1, v0, s[8:9] sc1
	s_waitcnt vmcnt(0)
	v_cmp_eq_u32_e32 vcc, 0, v1
	s_cbranch_vccnz .LBB0_486
	s_mov_b64 s[38:39], 0
	s_mov_b64 s[36:37], -1

.LBB0_732:
	global_load_dword v15, v16, s[4:5] sc1
	s_waitcnt lgkmcnt(0)
	global_load_dword v0, v16, s[8:9] sc1
	global_load_dword v1, v16, s[10:11] sc1
	global_load_dword v2, v16, s[14:15] sc1
	global_load_dword v3, v16, s[34:35] sc1
	global_load_dword v4, v16, s[36:37] sc1
	global_load_dword v5, v16, s[38:39] sc1
	global_load_dword v6, v16, s[40:41] sc1
	global_load_dword v7, v16, s[42:43] sc1
	global_load_dword v8, v16, s[44:45] sc1
	global_load_dword v9, v16, s[46:47] sc1
	global_load_dword v10, v16, s[48:49] sc1
	global_load_dword v11, v16, s[50:51] sc1
	global_load_dword v12, v16, s[90:91] sc1
	global_load_dword v13, v16, s[92:93] sc1
	global_load_dword v14, v16, s[94:95] sc1
	s_mov_b64 s[96:97], -1
	s_mov_b64 s[78:79], -1
	s_waitcnt vmcnt(14)
	v_add_u32_e32 v17, v0, v15
	s_waitcnt vmcnt(13)
	v_add_u32_e32 v17, v17, v1
	s_waitcnt vmcnt(12)
	v_add_u32_e32 v17, v17, v2
	s_waitcnt vmcnt(11)
	v_add_u32_e32 v17, v17, v3
	s_waitcnt vmcnt(10)
	v_add_u32_e32 v17, v17, v4
	s_waitcnt vmcnt(9)
	v_add_u32_e32 v17, v17, v5
	s_waitcnt vmcnt(8)
	v_add_u32_e32 v17, v17, v6
	s_waitcnt vmcnt(7)
	v_add_u32_e32 v17, v17, v7
	s_waitcnt vmcnt(6)
	v_add_u32_e32 v17, v17, v8
	s_waitcnt vmcnt(5)
	v_add_u32_e32 v17, v17, v9
	s_waitcnt vmcnt(4)
	v_add_u32_e32 v17, v17, v10
	s_waitcnt vmcnt(3)
	v_add_u32_e32 v17, v17, v11
	s_waitcnt vmcnt(2)
	v_add_u32_e32 v17, v17, v12
	s_waitcnt vmcnt(1)
	v_add_u32_e32 v17, v17, v13
	s_waitcnt vmcnt(0)
	v_add_u32_e32 v17, v17, v14
	v_cmp_eq_u32_e32 vcc, s13, v17
	s_cbranch_vccnz .LBB0_731
	s_and_b32 s17, s16, 0xff
	s_cmp_eq_u32 s17, 0
	s_mov_b64 s[84:85], -1
	s_nop 0
	s_cbranch_scc0 .LBB0_736
	global_load_dword v17, v16, s[2:3] sc1
	s_waitcnt vmcnt(0)
	v_cmp_eq_u32_e32 vcc, 0, v17
	s_cbranch_vccnz .LBB0_738
	s_mov_b64 s[84:85], 0

.LBB0_841:
	global_load_dword v15, v16, s[6:7] sc1
	s_waitcnt lgkmcnt(0)
	global_load_dword v0, v16, s[8:9] sc1
	global_load_dword v1, v16, s[14:15] sc1
	global_load_dword v2, v16, s[34:35] sc1
	global_load_dword v3, v16, s[36:37] sc1
	global_load_dword v4, v16, s[38:39] sc1
	global_load_dword v5, v16, s[40:41] sc1
	global_load_dword v6, v16, s[42:43] sc1
	global_load_dword v7, v16, s[44:45] sc1
	global_load_dword v8, v16, s[46:47] sc1
	global_load_dword v9, v16, s[48:49] sc1
	global_load_dword v10, v16, s[50:51] sc1
	global_load_dword v11, v16, s[90:91] sc1
	global_load_dword v12, v16, s[92:93] sc1
	global_load_dword v13, v16, s[94:95] sc1
	global_load_dword v14, v16, s[96:97] sc1
	s_mov_b64 s[78:79], -1
	s_mov_b64 s[84:85], -1
	s_waitcnt vmcnt(14)
	v_add_u32_e32 v17, v0, v15
	s_waitcnt vmcnt(13)
	v_add_u32_e32 v17, v17, v1
	s_waitcnt vmcnt(12)
	v_add_u32_e32 v17, v17, v2
	s_waitcnt vmcnt(11)
	v_add_u32_e32 v17, v17, v3
	s_waitcnt vmcnt(10)
	v_add_u32_e32 v17, v17, v4
	s_waitcnt vmcnt(9)
	v_add_u32_e32 v17, v17, v5
	s_waitcnt vmcnt(8)
	v_add_u32_e32 v17, v17, v6
	s_waitcnt vmcnt(7)
	v_add_u32_e32 v17, v17, v7
	s_waitcnt vmcnt(6)
	v_add_u32_e32 v17, v17, v8
	s_waitcnt vmcnt(5)
	v_add_u32_e32 v17, v17, v9
	s_waitcnt vmcnt(4)
	v_add_u32_e32 v17, v17, v10
	s_waitcnt vmcnt(3)
	v_add_u32_e32 v17, v17, v11
	s_waitcnt vmcnt(2)
	v_add_u32_e32 v17, v17, v12
	s_waitcnt vmcnt(1)
	v_add_u32_e32 v17, v17, v13
	s_waitcnt vmcnt(0)
	v_add_u32_e32 v17, v17, v14
	v_cmp_eq_u32_e32 vcc, s13, v17
	s_cbranch_vccnz .LBB0_840
	s_and_b32 s17, s16, 0xff
	s_cmp_eq_u32 s17, 0
	s_mov_b64 vcc, -1
	s_nop 0
	s_cbranch_scc0 .LBB0_845
	global_load_dword v17, v16, s[2:3] sc1
	s_waitcnt vmcnt(0)
	v_cmp_eq_u32_e32 vcc, 0, v17
	s_cbranch_vccnz .LBB0_847
	s_mov_b64 vcc, 0

.LBB0_859:
	s_and_b32 s16, s13, 0xff
	s_mov_b64 s[40:41], -1
	s_cmp_lg_u32 s16, 0
	s_mov_b64 s[44:45], -1
	s_nop 0
	s_cbranch_scc1 .LBB0_862
	global_load_dword v2, v0, s[14:15] sc1
	s_waitcnt vmcnt(0)
	v_cmp_eq_u32_e32 vcc, 0, v2
	s_cbranch_vccnz .LBB0_864
	s_mov_b64 s[44:45], 0
	s_mov_b64 s[42:43], -1

.LBB0_876:
	s_and_b32 s16, s13, 0xff
	s_cmp_lg_u32 s16, 0
	s_mov_b64 s[42:43], -1
	s_nop 0
	s_cbranch_scc1 .LBB0_879
	global_load_dword v1, v0, s[14:15] sc1
	s_waitcnt vmcnt(0)
	v_cmp_eq_u32_e32 vcc, 0, v1
	s_cbranch_vccnz .LBB0_881
	s_mov_b64 s[42:43], 0
	s_mov_b64 s[40:41], -1

.LBB0_916:
	global_load_dword v15, v16, s[6:7] sc1
	s_waitcnt lgkmcnt(0)
	global_load_dword v0, v16, s[8:9] sc1
	global_load_dword v1, v16, s[14:15] sc1
	global_load_dword v2, v16, s[34:35] sc1
	global_load_dword v3, v16, s[36:37] sc1
	global_load_dword v4, v16, s[38:39] sc1
	global_load_dword v5, v16, s[40:41] sc1
	global_load_dword v6, v16, s[42:43] sc1
	global_load_dword v7, v16, s[44:45] sc1
	global_load_dword v8, v16, s[46:47] sc1
	global_load_dword v9, v16, s[48:49] sc1
	global_load_dword v10, v16, s[50:51] sc1
	global_load_dword v11, v16, s[52:53] sc1
	global_load_dword v12, v16, s[56:57] sc1
	global_load_dword v13, v16, s[90:91] sc1
	global_load_dword v14, v16, s[92:93] sc1
	s_mov_b64 s[78:79], -1
	s_mov_b64 s[84:85], -1
	s_waitcnt vmcnt(14)
	v_add_u32_e32 v17, v0, v15
	s_waitcnt vmcnt(13)
	v_add_u32_e32 v17, v17, v1
	s_waitcnt vmcnt(12)
	v_add_u32_e32 v17, v17, v2
	s_waitcnt vmcnt(11)
	v_add_u32_e32 v17, v17, v3
	s_waitcnt vmcnt(10)
	v_add_u32_e32 v17, v17, v4
	s_waitcnt vmcnt(9)
	v_add_u32_e32 v17, v17, v5
	s_waitcnt vmcnt(8)
	v_add_u32_e32 v17, v17, v6
	s_waitcnt vmcnt(7)
	v_add_u32_e32 v17, v17, v7
	s_waitcnt vmcnt(6)
	v_add_u32_e32 v17, v17, v8
	s_waitcnt vmcnt(5)
	v_add_u32_e32 v17, v17, v9
	s_waitcnt vmcnt(4)
	v_add_u32_e32 v17, v17, v10
	s_waitcnt vmcnt(3)
	v_add_u32_e32 v17, v17, v11
	s_waitcnt vmcnt(2)
	v_add_u32_e32 v17, v17, v12
	s_waitcnt vmcnt(1)
	v_add_u32_e32 v17, v17, v13
	s_waitcnt vmcnt(0)
	v_add_u32_e32 v17, v17, v14
	v_cmp_eq_u32_e32 vcc, s13, v17
	s_cbranch_vccnz .LBB0_915
	s_and_b32 s17, s16, 0xff
	s_cmp_eq_u32 s17, 0
	s_mov_b64 s[94:95], -1
	s_nop 0
	s_cbranch_scc0 .LBB0_920
	global_load_dword v17, v16, s[4:5] sc1
	s_waitcnt vmcnt(0)
	v_cmp_eq_u32_e32 vcc, 0, v17
	s_cbranch_vccnz .LBB0_922
	s_mov_b64 s[94:95], 0

.LBB0_987:
	global_load_dword v15, v16, s[6:7] sc1
	s_waitcnt lgkmcnt(0)
	global_load_dword v0, v16, s[8:9] sc1
	global_load_dword v1, v16, s[14:15] sc1
	global_load_dword v2, v16, s[34:35] sc1
	global_load_dword v3, v16, s[36:37] sc1
	global_load_dword v4, v16, s[38:39] sc1
	global_load_dword v5, v16, s[40:41] sc1
	global_load_dword v6, v16, s[42:43] sc1
	global_load_dword v7, v16, s[44:45] sc1
	global_load_dword v8, v16, s[46:47] sc1
	global_load_dword v9, v16, s[48:49] sc1
	global_load_dword v10, v16, s[50:51] sc1
	global_load_dword v11, v16, s[52:53] sc1
	global_load_dword v12, v16, s[56:57] sc1
	global_load_dword v13, v16, s[88:89] sc1
	global_load_dword v14, v16, s[90:91] sc1
	s_mov_b64 s[78:79], -1
	s_mov_b64 s[84:85], -1
	s_waitcnt vmcnt(14)
	v_add_u32_e32 v17, v0, v15
	s_waitcnt vmcnt(13)
	v_add_u32_e32 v17, v17, v1
	s_waitcnt vmcnt(12)
	v_add_u32_e32 v17, v17, v2
	s_waitcnt vmcnt(11)
	v_add_u32_e32 v17, v17, v3
	s_waitcnt vmcnt(10)
	v_add_u32_e32 v17, v17, v4
	s_waitcnt vmcnt(9)
	v_add_u32_e32 v17, v17, v5
	s_waitcnt vmcnt(8)
	v_add_u32_e32 v17, v17, v6
	s_waitcnt vmcnt(7)
	v_add_u32_e32 v17, v17, v7
	s_waitcnt vmcnt(6)
	v_add_u32_e32 v17, v17, v8
	s_waitcnt vmcnt(5)
	v_add_u32_e32 v17, v17, v9
	s_waitcnt vmcnt(4)
	v_add_u32_e32 v17, v17, v10
	s_waitcnt vmcnt(3)
	v_add_u32_e32 v17, v17, v11
	s_waitcnt vmcnt(2)
	v_add_u32_e32 v17, v17, v12
	s_waitcnt vmcnt(1)
	v_add_u32_e32 v17, v17, v13
	s_waitcnt vmcnt(0)
	v_add_u32_e32 v17, v17, v14
	v_cmp_eq_u32_e32 vcc, s13, v17
	s_cbranch_vccnz .LBB0_986
	s_and_b32 s17, s16, 0xff
	s_cmp_eq_u32 s17, 0
	s_mov_b64 s[92:93], -1
	s_nop 0
	s_cbranch_scc0 .LBB0_991
	global_load_dword v17, v16, s[2:3] sc1
	s_waitcnt vmcnt(0)
	v_cmp_eq_u32_e32 vcc, 0, v17
	s_cbranch_vccnz .LBB0_993
	s_mov_b64 s[92:93], 0

.LBB0_1058:
	global_load_dword v15, v16, s[6:7] sc1
	s_waitcnt lgkmcnt(0)
	global_load_dword v0, v16, s[8:9] sc1
	global_load_dword v1, v16, s[14:15] sc1
	global_load_dword v2, v16, s[34:35] sc1
	global_load_dword v3, v16, s[36:37] sc1
	global_load_dword v4, v16, s[38:39] sc1
	global_load_dword v5, v16, s[40:41] sc1
	global_load_dword v6, v16, s[42:43] sc1
	global_load_dword v7, v16, s[44:45] sc1
	global_load_dword v8, v16, s[46:47] sc1
	global_load_dword v9, v16, s[48:49] sc1
	global_load_dword v10, v16, s[50:51] sc1
	global_load_dword v11, v16, s[56:57] sc1
	global_load_dword v12, v16, s[88:89] sc1
	global_load_dword v13, v16, s[90:91] sc1
	global_load_dword v14, v16, s[92:93] sc1
	s_mov_b64 s[78:79], -1
	s_mov_b64 s[84:85], -1
	s_waitcnt vmcnt(14)
	v_add_u32_e32 v17, v0, v15
	s_waitcnt vmcnt(13)
	v_add_u32_e32 v17, v17, v1
	s_waitcnt vmcnt(12)
	v_add_u32_e32 v17, v17, v2
	s_waitcnt vmcnt(11)
	v_add_u32_e32 v17, v17, v3
	s_waitcnt vmcnt(10)
	v_add_u32_e32 v17, v17, v4
	s_waitcnt vmcnt(9)
	v_add_u32_e32 v17, v17, v5
	s_waitcnt vmcnt(8)
	v_add_u32_e32 v17, v17, v6
	s_waitcnt vmcnt(7)
	v_add_u32_e32 v17, v17, v7
	s_waitcnt vmcnt(6)
	v_add_u32_e32 v17, v17, v8
	s_waitcnt vmcnt(5)
	v_add_u32_e32 v17, v17, v9
	s_waitcnt vmcnt(4)
	v_add_u32_e32 v17, v17, v10
	s_waitcnt vmcnt(3)
	v_add_u32_e32 v17, v17, v11
	s_waitcnt vmcnt(2)
	v_add_u32_e32 v17, v17, v12
	s_waitcnt vmcnt(1)
	v_add_u32_e32 v17, v17, v13
	s_waitcnt vmcnt(0)
	v_add_u32_e32 v17, v17, v14
	v_cmp_eq_u32_e32 vcc, s13, v17
	s_cbranch_vccnz .LBB0_1057
	s_and_b32 s17, s16, 0xff
	s_cmp_eq_u32 s17, 0
	s_mov_b64 s[94:95], -1
	s_nop 0
	s_cbranch_scc0 .LBB0_1062
	global_load_dword v17, v16, s[4:5] sc1
	s_waitcnt vmcnt(0)
	v_cmp_eq_u32_e32 vcc, 0, v17
	s_cbranch_vccnz .LBB0_1064
	s_mov_b64 s[94:95], 0

.LBB0_1339:
	global_load_dword v15, v16, s[4:5] sc1
	s_waitcnt lgkmcnt(0)
	global_load_dword v0, v16, s[8:9] sc1
	global_load_dword v1, v16, s[14:15] sc1
	global_load_dword v2, v16, s[34:35] sc1
	global_load_dword v3, v16, s[36:37] sc1
	global_load_dword v4, v16, s[38:39] sc1
	global_load_dword v5, v16, s[40:41] sc1
	global_load_dword v6, v16, s[42:43] sc1
	global_load_dword v7, v16, s[44:45] sc1
	global_load_dword v8, v16, s[46:47] sc1
	global_load_dword v9, v16, s[48:49] sc1
	global_load_dword v10, v16, s[50:51] sc1
	global_load_dword v11, v16, s[88:89] sc1
	global_load_dword v12, v16, s[90:91] sc1
	global_load_dword v13, v16, s[92:93] sc1
	global_load_dword v14, v16, s[94:95] sc1
	s_mov_b64 s[78:79], -1
	s_mov_b64 s[84:85], -1
	s_waitcnt vmcnt(14)
	v_add_u32_e32 v17, v0, v15
	s_waitcnt vmcnt(13)
	v_add_u32_e32 v17, v17, v1
	s_waitcnt vmcnt(12)
	v_add_u32_e32 v17, v17, v2
	s_waitcnt vmcnt(11)
	v_add_u32_e32 v17, v17, v3
	s_waitcnt vmcnt(10)
	v_add_u32_e32 v17, v17, v4
	s_waitcnt vmcnt(9)
	v_add_u32_e32 v17, v17, v5
	s_waitcnt vmcnt(8)
	v_add_u32_e32 v17, v17, v6
	s_waitcnt vmcnt(7)
	v_add_u32_e32 v17, v17, v7
	s_waitcnt vmcnt(6)
	v_add_u32_e32 v17, v17, v8
	s_waitcnt vmcnt(5)
	v_add_u32_e32 v17, v17, v9
	s_waitcnt vmcnt(4)
	v_add_u32_e32 v17, v17, v10
	s_waitcnt vmcnt(3)
	v_add_u32_e32 v17, v17, v11
	s_waitcnt vmcnt(2)
	v_add_u32_e32 v17, v17, v12
	s_waitcnt vmcnt(1)
	v_add_u32_e32 v17, v17, v13
	s_waitcnt vmcnt(0)
	v_add_u32_e32 v17, v17, v14
	v_cmp_eq_u32_e32 vcc, s13, v17
	s_cbranch_vccnz .LBB0_1338
	s_and_b32 s17, s16, 0xff
	s_cmp_eq_u32 s17, 0
	s_mov_b64 s[96:97], -1
	s_nop 0
	s_cbranch_scc0 .LBB0_1343
	global_load_dword v17, v16, s[2:3] sc1
	s_waitcnt vmcnt(0)
	v_cmp_eq_u32_e32 vcc, 0, v17
	s_cbranch_vccnz .LBB0_1345
	s_mov_b64 s[96:97], 0

.LBB0_1468:
	global_load_dword v15, v16, s[6:7] sc1
	s_waitcnt lgkmcnt(0)
	global_load_dword v0, v16, s[8:9] sc1
	global_load_dword v1, v16, s[14:15] sc1
	global_load_dword v2, v16, s[16:17] sc1
	global_load_dword v3, v16, s[18:19] sc1
	global_load_dword v4, v16, s[22:23] sc1
	global_load_dword v5, v16, s[28:29] sc1
	global_load_dword v6, v16, s[34:35] sc1
	global_load_dword v7, v16, s[36:37] sc1
	global_load_dword v8, v16, s[38:39] sc1
	global_load_dword v9, v16, s[40:41] sc1
	global_load_dword v10, v16, s[42:43] sc1
	global_load_dword v11, v16, s[44:45] sc1
	global_load_dword v12, v16, s[46:47] sc1
	global_load_dword v13, v16, s[48:49] sc1
	global_load_dword v14, v16, s[50:51] sc1
	s_mov_b64 s[64:65], -1
	s_mov_b64 s[66:67], -1
	s_waitcnt vmcnt(14)
	v_add_u32_e32 v17, v0, v15
	s_waitcnt vmcnt(13)
	v_add_u32_e32 v17, v17, v1
	s_waitcnt vmcnt(12)
	v_add_u32_e32 v17, v17, v2
	s_waitcnt vmcnt(11)
	v_add_u32_e32 v17, v17, v3
	s_waitcnt vmcnt(10)
	v_add_u32_e32 v17, v17, v4
	s_waitcnt vmcnt(9)
	v_add_u32_e32 v17, v17, v5
	s_waitcnt vmcnt(8)
	v_add_u32_e32 v17, v17, v6
	s_waitcnt vmcnt(7)
	v_add_u32_e32 v17, v17, v7
	s_waitcnt vmcnt(6)
	v_add_u32_e32 v17, v17, v8
	s_waitcnt vmcnt(5)
	v_add_u32_e32 v17, v17, v9
	s_waitcnt vmcnt(4)
	v_add_u32_e32 v17, v17, v10
	s_waitcnt vmcnt(3)
	v_add_u32_e32 v17, v17, v11
	s_waitcnt vmcnt(2)
	v_add_u32_e32 v17, v17, v12
	s_waitcnt vmcnt(1)
	v_add_u32_e32 v17, v17, v13
	s_waitcnt vmcnt(0)
	v_add_u32_e32 v17, v17, v14
	v_cmp_eq_u32_e32 vcc, s13, v17
	s_cbranch_vccnz .LBB0_1467
	s_and_b32 s21, s20, 0xff
	s_cmp_eq_u32 s21, 0
	s_mov_b64 s[78:79], -1
	s_nop 0
	s_cbranch_scc0 .LBB0_1472
	global_load_dword v17, v16, s[4:5] sc1
	s_waitcnt vmcnt(0)
	v_cmp_eq_u32_e32 vcc, 0, v17
	s_cbranch_vccnz .LBB0_1474
	s_mov_b64 s[78:79], 0

.LBB0_1486:
	s_and_b32 s20, s13, 0xff
	s_mov_b64 s[28:29], -1
	s_cmp_lg_u32 s20, 0
	s_mov_b64 s[36:37], -1
	s_nop 0
	s_cbranch_scc1 .LBB0_1489
	global_load_dword v2, v0, s[14:15] sc1
	s_waitcnt vmcnt(0)
	v_cmp_eq_u32_e32 vcc, 0, v2
	s_cbranch_vccnz .LBB0_1491
	s_mov_b64 s[36:37], 0
	s_mov_b64 s[34:35], -1

.LBB0_1503:
	s_and_b32 s20, s13, 0xff
	s_cmp_lg_u32 s20, 0
	s_mov_b64 s[34:35], -1
	s_nop 0
	s_cbranch_scc1 .LBB0_1506
	global_load_dword v1, v0, s[14:15] sc1
	s_waitcnt vmcnt(0)
	v_cmp_eq_u32_e32 vcc, 0, v1
	s_cbranch_vccnz .LBB0_1508
	s_mov_b64 s[34:35], 0
	s_mov_b64 s[28:29], -1

.LBB0_1539:
	global_load_dword v15, v16, s[4:5] sc1
	s_waitcnt lgkmcnt(0)
	global_load_dword v0, v16, s[6:7] sc1
	global_load_dword v1, v16, s[8:9] sc1
	global_load_dword v2, v16, s[16:17] sc1
	global_load_dword v3, v16, s[18:19] sc1
	global_load_dword v4, v16, s[22:23] sc1
	global_load_dword v5, v16, s[28:29] sc1
	global_load_dword v6, v16, s[34:35] sc1
	global_load_dword v7, v16, s[36:37] sc1
	global_load_dword v8, v16, s[38:39] sc1
	global_load_dword v9, v16, s[40:41] sc1
	global_load_dword v10, v16, s[42:43] sc1
	global_load_dword v11, v16, s[44:45] sc1
	global_load_dword v12, v16, s[46:47] sc1
	global_load_dword v13, v16, s[48:49] sc1
	global_load_dword v14, v16, s[50:51] sc1
	s_mov_b64 s[64:65], -1
	s_mov_b64 s[66:67], -1
	s_waitcnt vmcnt(14)
	v_add_u32_e32 v17, v0, v15
	s_waitcnt vmcnt(13)
	v_add_u32_e32 v17, v17, v1
	s_waitcnt vmcnt(12)
	v_add_u32_e32 v17, v17, v2
	s_waitcnt vmcnt(11)
	v_add_u32_e32 v17, v17, v3
	s_waitcnt vmcnt(10)
	v_add_u32_e32 v17, v17, v4
	s_waitcnt vmcnt(9)
	v_add_u32_e32 v17, v17, v5
	s_waitcnt vmcnt(8)
	v_add_u32_e32 v17, v17, v6
	s_waitcnt vmcnt(7)
	v_add_u32_e32 v17, v17, v7
	s_waitcnt vmcnt(6)
	v_add_u32_e32 v17, v17, v8
	s_waitcnt vmcnt(5)
	v_add_u32_e32 v17, v17, v9
	s_waitcnt vmcnt(4)
	v_add_u32_e32 v17, v17, v10
	s_waitcnt vmcnt(3)
	v_add_u32_e32 v17, v17, v11
	s_waitcnt vmcnt(2)
	v_add_u32_e32 v17, v17, v12
	s_waitcnt vmcnt(1)
	v_add_u32_e32 v17, v17, v13
	s_waitcnt vmcnt(0)
	v_add_u32_e32 v17, v17, v14
	v_cmp_eq_u32_e32 vcc, s13, v17
	s_cbranch_vccnz .LBB0_1538
	s_and_b32 s21, s20, 0xff
	s_cmp_eq_u32 s21, 0
	s_mov_b64 s[78:79], -1
	s_nop 0
	s_cbranch_scc0 .LBB0_1543
	global_load_dword v17, v16, s[2:3] sc1
	s_waitcnt vmcnt(0)
	v_cmp_eq_u32_e32 vcc, 0, v17
	s_cbranch_vccnz .LBB0_1545
	s_mov_b64 s[78:79], 0

.LBB0_1557:
	s_and_b32 s20, s13, 0xff
	s_mov_b64 s[28:29], -1
	s_cmp_lg_u32 s20, 0
	s_mov_b64 s[36:37], -1
	s_nop 0
	s_cbranch_scc1 .LBB0_1560
	global_load_dword v2, v0, s[8:9] sc1
	s_waitcnt vmcnt(0)
	v_cmp_eq_u32_e32 vcc, 0, v2
	s_cbranch_vccnz .LBB0_1562
	s_mov_b64 s[36:37], 0
	s_mov_b64 s[34:35], -1

.LBB0_1574:
	s_and_b32 s20, s13, 0xff
	s_cmp_lg_u32 s20, 0
	s_mov_b64 s[34:35], -1
	s_nop 0
	s_cbranch_scc1 .LBB0_1577
	global_load_dword v1, v0, s[8:9] sc1
	s_waitcnt vmcnt(0)
	v_cmp_eq_u32_e32 vcc, 0, v1
	s_cbranch_vccnz .LBB0_1579
	s_mov_b64 s[34:35], 0
	s_mov_b64 s[28:29], -1

.LBB0_1616:
	global_load_dword v15, v16, s[4:5] sc1
	s_waitcnt lgkmcnt(0)
	global_load_dword v0, v16, s[8:9] sc1
	global_load_dword v1, v16, s[14:15] sc1
	global_load_dword v2, v16, s[16:17] sc1
	global_load_dword v3, v16, s[18:19] sc1
	global_load_dword v4, v16, s[22:23] sc1
	global_load_dword v5, v16, s[28:29] sc1
	global_load_dword v6, v16, s[34:35] sc1
	global_load_dword v7, v16, s[36:37] sc1
	global_load_dword v8, v16, s[38:39] sc1
	global_load_dword v9, v16, s[40:41] sc1
	global_load_dword v10, v16, s[42:43] sc1
	global_load_dword v11, v16, s[44:45] sc1
	global_load_dword v12, v16, s[46:47] sc1
	global_load_dword v13, v16, s[48:49] sc1
	global_load_dword v14, v16, s[50:51] sc1
	s_mov_b64 s[64:65], -1
	s_mov_b64 s[66:67], -1
	s_waitcnt vmcnt(14)
	v_add_u32_e32 v17, v0, v15
	s_waitcnt vmcnt(13)
	v_add_u32_e32 v17, v17, v1
	s_waitcnt vmcnt(12)
	v_add_u32_e32 v17, v17, v2
	s_waitcnt vmcnt(11)
	v_add_u32_e32 v17, v17, v3
	s_waitcnt vmcnt(10)
	v_add_u32_e32 v17, v17, v4
	s_waitcnt vmcnt(9)
	v_add_u32_e32 v17, v17, v5
	s_waitcnt vmcnt(8)
	v_add_u32_e32 v17, v17, v6
	s_waitcnt vmcnt(7)
	v_add_u32_e32 v17, v17, v7
	s_waitcnt vmcnt(6)
	v_add_u32_e32 v17, v17, v8
	s_waitcnt vmcnt(5)
	v_add_u32_e32 v17, v17, v9
	s_waitcnt vmcnt(4)
	v_add_u32_e32 v17, v17, v10
	s_waitcnt vmcnt(3)
	v_add_u32_e32 v17, v17, v11
	s_waitcnt vmcnt(2)
	v_add_u32_e32 v17, v17, v12
	s_waitcnt vmcnt(1)
	v_add_u32_e32 v17, v17, v13
	s_waitcnt vmcnt(0)
	v_add_u32_e32 v17, v17, v14
	v_cmp_eq_u32_e32 vcc, s13, v17
	s_cbranch_vccnz .LBB0_1615
	s_and_b32 s21, s20, 0xff
	s_cmp_eq_u32 s21, 0
	s_mov_b64 s[78:79], -1
	s_nop 0
	s_cbranch_scc0 .LBB0_1620
	global_load_dword v17, v16, s[2:3] sc1
	s_waitcnt vmcnt(0)
	v_cmp_eq_u32_e32 vcc, 0, v17
	s_cbranch_vccnz .LBB0_1622
	s_mov_b64 s[78:79], 0

.LBB0_1890:
	global_load_dword v15, v16, s[6:7] sc1
	s_waitcnt lgkmcnt(0)
	global_load_dword v0, v16, s[8:9] sc1
	global_load_dword v1, v16, s[14:15] sc1
	global_load_dword v2, v16, s[16:17] sc1
	global_load_dword v3, v16, s[18:19] sc1
	global_load_dword v4, v16, s[22:23] sc1
	global_load_dword v5, v16, s[28:29] sc1
	global_load_dword v6, v16, s[34:35] sc1
	global_load_dword v7, v16, s[36:37] sc1
	global_load_dword v8, v16, s[38:39] sc1
	global_load_dword v9, v16, s[40:41] sc1
	global_load_dword v10, v16, s[42:43] sc1
	global_load_dword v11, v16, s[44:45] sc1
	global_load_dword v12, v16, s[46:47] sc1
	global_load_dword v13, v16, s[48:49] sc1
	global_load_dword v14, v16, s[50:51] sc1
	s_mov_b64 s[62:63], -1
	s_mov_b64 s[64:65], -1
	s_waitcnt vmcnt(14)
	v_add_u32_e32 v17, v0, v15
	s_waitcnt vmcnt(13)
	v_add_u32_e32 v17, v17, v1
	s_waitcnt vmcnt(12)
	v_add_u32_e32 v17, v17, v2
	s_waitcnt vmcnt(11)
	v_add_u32_e32 v17, v17, v3
	s_waitcnt vmcnt(10)
	v_add_u32_e32 v17, v17, v4
	s_waitcnt vmcnt(9)
	v_add_u32_e32 v17, v17, v5
	s_waitcnt vmcnt(8)
	v_add_u32_e32 v17, v17, v6
	s_waitcnt vmcnt(7)
	v_add_u32_e32 v17, v17, v7
	s_waitcnt vmcnt(6)
	v_add_u32_e32 v17, v17, v8
	s_waitcnt vmcnt(5)
	v_add_u32_e32 v17, v17, v9
	s_waitcnt vmcnt(4)
	v_add_u32_e32 v17, v17, v10
	s_waitcnt vmcnt(3)
	v_add_u32_e32 v17, v17, v11
	s_waitcnt vmcnt(2)
	v_add_u32_e32 v17, v17, v12
	s_waitcnt vmcnt(1)
	v_add_u32_e32 v17, v17, v13
	s_waitcnt vmcnt(0)
	v_add_u32_e32 v17, v17, v14
	v_cmp_eq_u32_e32 vcc, s13, v17
	s_cbranch_vccnz .LBB0_1889
	s_and_b32 s21, s20, 0xff
	s_cmp_eq_u32 s21, 0
	s_mov_b64 s[66:67], -1
	s_nop 0
	s_cbranch_scc0 .LBB0_1894
	global_load_dword v17, v16, s[2:3] sc1
	s_waitcnt vmcnt(0)
	v_cmp_eq_u32_e32 vcc, 0, v17
	s_cbranch_vccnz .LBB0_1896
	s_mov_b64 s[66:67], 0

.LBB0_1961:
	global_load_dword v15, v16, s[6:7] sc1
	s_waitcnt lgkmcnt(0)
	global_load_dword v0, v16, s[8:9] sc1
	global_load_dword v1, v16, s[14:15] sc1
	global_load_dword v2, v16, s[16:17] sc1
	global_load_dword v3, v16, s[18:19] sc1
	global_load_dword v4, v16, s[22:23] sc1
	global_load_dword v5, v16, s[28:29] sc1
	global_load_dword v6, v16, s[34:35] sc1
	global_load_dword v7, v16, s[36:37] sc1
	global_load_dword v8, v16, s[38:39] sc1
	global_load_dword v9, v16, s[40:41] sc1
	global_load_dword v10, v16, s[42:43] sc1
	global_load_dword v11, v16, s[44:45] sc1
	global_load_dword v12, v16, s[46:47] sc1
	global_load_dword v13, v16, s[48:49] sc1
	global_load_dword v14, v16, s[50:51] sc1
	s_mov_b64 s[62:63], -1
	s_mov_b64 s[64:65], -1
	s_waitcnt vmcnt(14)
	v_add_u32_e32 v17, v0, v15
	s_waitcnt vmcnt(13)
	v_add_u32_e32 v17, v17, v1
	s_waitcnt vmcnt(12)
	v_add_u32_e32 v17, v17, v2
	s_waitcnt vmcnt(11)
	v_add_u32_e32 v17, v17, v3
	s_waitcnt vmcnt(10)
	v_add_u32_e32 v17, v17, v4
	s_waitcnt vmcnt(9)
	v_add_u32_e32 v17, v17, v5
	s_waitcnt vmcnt(8)
	v_add_u32_e32 v17, v17, v6
	s_waitcnt vmcnt(7)
	v_add_u32_e32 v17, v17, v7
	s_waitcnt vmcnt(6)
	v_add_u32_e32 v17, v17, v8
	s_waitcnt vmcnt(5)
	v_add_u32_e32 v17, v17, v9
	s_waitcnt vmcnt(4)
	v_add_u32_e32 v17, v17, v10
	s_waitcnt vmcnt(3)
	v_add_u32_e32 v17, v17, v11
	s_waitcnt vmcnt(2)
	v_add_u32_e32 v17, v17, v12
	s_waitcnt vmcnt(1)
	v_add_u32_e32 v17, v17, v13
	s_waitcnt vmcnt(0)
	v_add_u32_e32 v17, v17, v14
	v_cmp_eq_u32_e32 vcc, s13, v17
	s_cbranch_vccnz .LBB0_1960
	s_and_b32 s21, s20, 0xff
	s_cmp_eq_u32 s21, 0
	s_mov_b64 s[66:67], -1
	s_nop 0
	s_cbranch_scc0 .LBB0_1965
	global_load_dword v17, v16, s[4:5] sc1
	s_waitcnt vmcnt(0)
	v_cmp_eq_u32_e32 vcc, 0, v17
	s_cbranch_vccnz .LBB0_1967
	s_mov_b64 s[66:67], 0

.LBB0_2078:
	global_load_dword v15, v16, s[6:7] sc1
	s_waitcnt lgkmcnt(0)
	global_load_dword v0, v16, s[8:9] sc1
	global_load_dword v1, v16, s[14:15] sc1
	global_load_dword v2, v16, s[16:17] sc1
	global_load_dword v3, v16, s[18:19] sc1
	global_load_dword v4, v16, s[22:23] sc1
	global_load_dword v5, v16, s[28:29] sc1
	global_load_dword v6, v16, s[34:35] sc1
	global_load_dword v7, v16, s[36:37] sc1
	global_load_dword v8, v16, s[38:39] sc1
	global_load_dword v9, v16, s[40:41] sc1
	global_load_dword v10, v16, s[42:43] sc1
	global_load_dword v11, v16, s[44:45] sc1
	global_load_dword v12, v16, s[46:47] sc1
	global_load_dword v13, v16, s[48:49] sc1
	global_load_dword v14, v16, s[50:51] sc1
	s_mov_b64 s[60:61], -1
	s_mov_b64 s[62:63], -1
	s_waitcnt vmcnt(14)
	v_add_u32_e32 v17, v0, v15
	s_waitcnt vmcnt(13)
	v_add_u32_e32 v17, v17, v1
	s_waitcnt vmcnt(12)
	v_add_u32_e32 v17, v17, v2
	s_waitcnt vmcnt(11)
	v_add_u32_e32 v17, v17, v3
	s_waitcnt vmcnt(10)
	v_add_u32_e32 v17, v17, v4
	s_waitcnt vmcnt(9)
	v_add_u32_e32 v17, v17, v5
	s_waitcnt vmcnt(8)
	v_add_u32_e32 v17, v17, v6
	s_waitcnt vmcnt(7)
	v_add_u32_e32 v17, v17, v7
	s_waitcnt vmcnt(6)
	v_add_u32_e32 v17, v17, v8
	s_waitcnt vmcnt(5)
	v_add_u32_e32 v17, v17, v9
	s_waitcnt vmcnt(4)
	v_add_u32_e32 v17, v17, v10
	s_waitcnt vmcnt(3)
	v_add_u32_e32 v17, v17, v11
	s_waitcnt vmcnt(2)
	v_add_u32_e32 v17, v17, v12
	s_waitcnt vmcnt(1)
	v_add_u32_e32 v17, v17, v13
	s_waitcnt vmcnt(0)
	v_add_u32_e32 v17, v17, v14
	v_cmp_eq_u32_e32 vcc, s13, v17
	s_cbranch_vccnz .LBB0_2077
	s_and_b32 s21, s20, 0xff
	s_cmp_eq_u32 s21, 0
	s_mov_b64 s[64:65], -1
	s_nop 0
	s_cbranch_scc0 .LBB0_2082
	global_load_dword v17, v16, s[2:3] sc1
	s_waitcnt vmcnt(0)
	v_cmp_eq_u32_e32 vcc, 0, v17
	s_cbranch_vccnz .LBB0_2084
	s_mov_b64 s[64:65], 0

.LBB0_2161:
	global_load_dword v15, v16, s[4:5] sc1
	s_waitcnt lgkmcnt(0)
	global_load_dword v0, v16, s[8:9] sc1
	global_load_dword v1, v16, s[14:15] sc1
	global_load_dword v2, v16, s[16:17] sc1
	global_load_dword v3, v16, s[18:19] sc1
	global_load_dword v4, v16, s[22:23] sc1
	global_load_dword v5, v16, s[28:29] sc1
	global_load_dword v6, v16, s[34:35] sc1
	global_load_dword v7, v16, s[36:37] sc1
	global_load_dword v8, v16, s[38:39] sc1
	global_load_dword v9, v16, s[40:41] sc1
	global_load_dword v10, v16, s[42:43] sc1
	global_load_dword v11, v16, s[44:45] sc1
	global_load_dword v12, v16, s[46:47] sc1
	global_load_dword v13, v16, s[48:49] sc1
	global_load_dword v14, v16, s[50:51] sc1
	s_mov_b64 s[60:61], -1
	s_mov_b64 s[62:63], -1
	s_waitcnt vmcnt(14)
	v_add_u32_e32 v17, v0, v15
	s_waitcnt vmcnt(13)
	v_add_u32_e32 v17, v17, v1
	s_waitcnt vmcnt(12)
	v_add_u32_e32 v17, v17, v2
	s_waitcnt vmcnt(11)
	v_add_u32_e32 v17, v17, v3
	s_waitcnt vmcnt(10)
	v_add_u32_e32 v17, v17, v4
	s_waitcnt vmcnt(9)
	v_add_u32_e32 v17, v17, v5
	s_waitcnt vmcnt(8)
	v_add_u32_e32 v17, v17, v6
	s_waitcnt vmcnt(7)
	v_add_u32_e32 v17, v17, v7
	s_waitcnt vmcnt(6)
	v_add_u32_e32 v17, v17, v8
	s_waitcnt vmcnt(5)
	v_add_u32_e32 v17, v17, v9
	s_waitcnt vmcnt(4)
	v_add_u32_e32 v17, v17, v10
	s_waitcnt vmcnt(3)
	v_add_u32_e32 v17, v17, v11
	s_waitcnt vmcnt(2)
	v_add_u32_e32 v17, v17, v12
	s_waitcnt vmcnt(1)
	v_add_u32_e32 v17, v17, v13
	s_waitcnt vmcnt(0)
	v_add_u32_e32 v17, v17, v14
	v_cmp_eq_u32_e32 vcc, s13, v17
	s_cbranch_vccnz .LBB0_2160
	s_and_b32 s21, s20, 0xff
	s_cmp_eq_u32 s21, 0
	s_mov_b64 s[64:65], -1
	s_nop 0
	s_cbranch_scc0 .LBB0_2165
	global_load_dword v17, v16, s[2:3] sc1
	s_waitcnt vmcnt(0)
	v_cmp_eq_u32_e32 vcc, 0, v17
	s_cbranch_vccnz .LBB0_2167
	s_mov_b64 s[64:65], 0

.LBB0_2232:
	global_load_dword v15, v16, s[6:7] sc1
	s_waitcnt lgkmcnt(0)
	global_load_dword v0, v16, s[8:9] sc1
	global_load_dword v1, v16, s[14:15] sc1
	global_load_dword v2, v16, s[16:17] sc1
	global_load_dword v3, v16, s[18:19] sc1
	global_load_dword v4, v16, s[20:21] sc1
	global_load_dword v5, v16, s[22:23] sc1
	global_load_dword v6, v16, s[28:29] sc1
	global_load_dword v7, v16, s[34:35] sc1
	global_load_dword v8, v16, s[36:37] sc1
	global_load_dword v9, v16, s[38:39] sc1
	global_load_dword v10, v16, s[40:41] sc1
	global_load_dword v11, v16, s[42:43] sc1
	global_load_dword v12, v16, s[44:45] sc1
	global_load_dword v13, v16, s[46:47] sc1
	global_load_dword v14, v16, s[48:49] sc1
	s_mov_b64 s[50:51], -1
	s_mov_b64 s[56:57], -1
	s_waitcnt vmcnt(14)
	v_add_u32_e32 v17, v0, v15
	s_waitcnt vmcnt(13)
	v_add_u32_e32 v17, v17, v1
	s_waitcnt vmcnt(12)
	v_add_u32_e32 v17, v17, v2
	s_waitcnt vmcnt(11)
	v_add_u32_e32 v17, v17, v3
	s_waitcnt vmcnt(10)
	v_add_u32_e32 v17, v17, v4
	s_waitcnt vmcnt(9)
	v_add_u32_e32 v17, v17, v5
	s_waitcnt vmcnt(8)
	v_add_u32_e32 v17, v17, v6
	s_waitcnt vmcnt(7)
	v_add_u32_e32 v17, v17, v7
	s_waitcnt vmcnt(6)
	v_add_u32_e32 v17, v17, v8
	s_waitcnt vmcnt(5)
	v_add_u32_e32 v17, v17, v9
	s_waitcnt vmcnt(4)
	v_add_u32_e32 v17, v17, v10
	s_waitcnt vmcnt(3)
	v_add_u32_e32 v17, v17, v11
	s_waitcnt vmcnt(2)
	v_add_u32_e32 v17, v17, v12
	s_waitcnt vmcnt(1)
	v_add_u32_e32 v17, v17, v13
	s_waitcnt vmcnt(0)
	v_add_u32_e32 v17, v17, v14
	v_cmp_eq_u32_e32 vcc, s13, v17
	s_cbranch_vccnz .LBB0_2231
	s_and_b32 s25, s24, 0xff
	s_cmp_eq_u32 s25, 0
	s_mov_b64 s[60:61], -1
	s_nop 0
	s_cbranch_scc0 .LBB0_2236
	global_load_dword v17, v16, s[4:5] sc1
	s_waitcnt vmcnt(0)
	v_cmp_eq_u32_e32 vcc, 0, v17
	s_cbranch_vccnz .LBB0_2238
	s_mov_b64 s[60:61], 0

.LBB0_2250:
	s_and_b32 s24, s13, 0xff
	s_mov_b64 s[22:23], -1
	s_cmp_lg_u32 s24, 0
	s_mov_b64 s[34:35], -1
	s_nop 0
	s_cbranch_scc1 .LBB0_2253
	global_load_dword v2, v0, s[14:15] sc1
	s_waitcnt vmcnt(0)
	v_cmp_eq_u32_e32 vcc, 0, v2
	s_cbranch_vccnz .LBB0_2255
	s_mov_b64 s[34:35], 0
	s_mov_b64 s[28:29], -1

.LBB0_2267:
	s_and_b32 s22, s13, 0xff
	s_cmp_lg_u32 s22, 0
	s_mov_b64 s[28:29], -1
	s_nop 0
	s_cbranch_scc1 .LBB0_2270
	global_load_dword v1, v0, s[14:15] sc1
	s_waitcnt vmcnt(0)
	v_cmp_eq_u32_e32 vcc, 0, v1
	s_cbranch_vccnz .LBB0_2272
	s_mov_b64 s[28:29], 0
	s_mov_b64 s[22:23], -1

.LBB0_2439:
	global_load_dword v15, v16, s[6:7] sc1
	s_waitcnt lgkmcnt(0)
	global_load_dword v0, v16, s[8:9] sc1
	global_load_dword v1, v16, s[14:15] sc1
	global_load_dword v2, v16, s[16:17] sc1
	global_load_dword v3, v16, s[18:19] sc1
	global_load_dword v4, v16, s[20:21] sc1
	global_load_dword v5, v16, s[22:23] sc1
	global_load_dword v6, v16, s[28:29] sc1
	global_load_dword v7, v16, s[34:35] sc1
	global_load_dword v8, v16, s[36:37] sc1
	global_load_dword v9, v16, s[38:39] sc1
	global_load_dword v10, v16, s[40:41] sc1
	global_load_dword v11, v16, s[42:43] sc1
	global_load_dword v12, v16, s[44:45] sc1
	global_load_dword v13, v16, s[46:47] sc1
	global_load_dword v14, v16, s[48:49] sc1
	s_mov_b64 s[50:51], -1
	s_mov_b64 s[54:55], -1
	s_waitcnt vmcnt(14)
	v_add_u32_e32 v17, v0, v15
	s_waitcnt vmcnt(13)
	v_add_u32_e32 v17, v17, v1
	s_waitcnt vmcnt(12)
	v_add_u32_e32 v17, v17, v2
	s_waitcnt vmcnt(11)
	v_add_u32_e32 v17, v17, v3
	s_waitcnt vmcnt(10)
	v_add_u32_e32 v17, v17, v4
	s_waitcnt vmcnt(9)
	v_add_u32_e32 v17, v17, v5
	s_waitcnt vmcnt(8)
	v_add_u32_e32 v17, v17, v6
	s_waitcnt vmcnt(7)
	v_add_u32_e32 v17, v17, v7
	s_waitcnt vmcnt(6)
	v_add_u32_e32 v17, v17, v8
	s_waitcnt vmcnt(5)
	v_add_u32_e32 v17, v17, v9
	s_waitcnt vmcnt(4)
	v_add_u32_e32 v17, v17, v10
	s_waitcnt vmcnt(3)
	v_add_u32_e32 v17, v17, v11
	s_waitcnt vmcnt(2)
	v_add_u32_e32 v17, v17, v12
	s_waitcnt vmcnt(1)
	v_add_u32_e32 v17, v17, v13
	s_waitcnt vmcnt(0)
	v_add_u32_e32 v17, v17, v14
	v_cmp_eq_u32_e32 vcc, s13, v17
	s_cbranch_vccnz .LBB0_2438
	s_and_b32 s25, s24, 0xff
	s_cmp_eq_u32 s25, 0
	s_mov_b64 s[56:57], -1
	s_nop 0
	s_cbranch_scc0 .LBB0_2443
	global_load_dword v17, v16, s[4:5] sc1
	s_waitcnt vmcnt(0)
	v_cmp_eq_u32_e32 vcc, 0, v17
	s_cbranch_vccnz .LBB0_2445
	s_mov_b64 s[56:57], 0

.LBB0_2504:
	global_load_dword v15, v16, s[6:7] sc1
	s_waitcnt lgkmcnt(0)
	global_load_dword v0, v16, s[8:9] sc1
	global_load_dword v1, v16, s[14:15] sc1
	global_load_dword v2, v16, s[16:17] sc1
	global_load_dword v3, v16, s[18:19] sc1
	global_load_dword v4, v16, s[20:21] sc1
	global_load_dword v5, v16, s[22:23] sc1
	global_load_dword v6, v16, s[24:25] sc1
	global_load_dword v7, v16, s[26:27] sc1
	global_load_dword v8, v16, s[28:29] sc1
	global_load_dword v9, v16, s[34:35] sc1
	global_load_dword v10, v16, s[36:37] sc1
	global_load_dword v11, v16, s[38:39] sc1
	global_load_dword v12, v16, s[40:41] sc1
	global_load_dword v13, v16, s[42:43] sc1
	global_load_dword v14, v16, s[44:45] sc1
	s_mov_b64 s[46:47], -1
	s_mov_b64 s[48:49], -1
	s_waitcnt vmcnt(14)
	v_add_u32_e32 v17, v0, v15
	s_waitcnt vmcnt(13)
	v_add_u32_e32 v17, v17, v1
	s_waitcnt vmcnt(12)
	v_add_u32_e32 v17, v17, v2
	s_waitcnt vmcnt(11)
	v_add_u32_e32 v17, v17, v3
	s_waitcnt vmcnt(10)
	v_add_u32_e32 v17, v17, v4
	s_waitcnt vmcnt(9)
	v_add_u32_e32 v17, v17, v5
	s_waitcnt vmcnt(8)
	v_add_u32_e32 v17, v17, v6
	s_waitcnt vmcnt(7)
	v_add_u32_e32 v17, v17, v7
	s_waitcnt vmcnt(6)
	v_add_u32_e32 v17, v17, v8
	s_waitcnt vmcnt(5)
	v_add_u32_e32 v17, v17, v9
	s_waitcnt vmcnt(4)
	v_add_u32_e32 v17, v17, v10
	s_waitcnt vmcnt(3)
	v_add_u32_e32 v17, v17, v11
	s_waitcnt vmcnt(2)
	v_add_u32_e32 v17, v17, v12
	s_waitcnt vmcnt(1)
	v_add_u32_e32 v17, v17, v13
	s_waitcnt vmcnt(0)
	v_add_u32_e32 v17, v17, v14
	v_cmp_eq_u32_e32 vcc, s13, v17
	s_cbranch_vccnz .LBB0_2503
	s_and_b32 s31, s30, 0xff
	s_cmp_eq_u32 s31, 0
	s_mov_b64 s[50:51], -1
	s_nop 0
	s_cbranch_scc0 .LBB0_2508
	global_load_dword v17, v16, s[4:5] sc1
	s_waitcnt vmcnt(0)
	v_cmp_eq_u32_e32 vcc, 0, v17
	s_cbranch_vccnz .LBB0_2510
	s_mov_b64 s[50:51], 0

.LBB0_2522:
	s_and_b32 s24, s13, 0xff
	s_mov_b64 s[22:23], -1
	s_cmp_lg_u32 s24, 0
	s_mov_b64 s[26:27], -1
	s_nop 0
	s_cbranch_scc1 .LBB0_2525
	global_load_dword v2, v0, s[14:15] sc1
	s_waitcnt vmcnt(0)
	v_cmp_eq_u32_e32 vcc, 0, v2
	s_cbranch_vccnz .LBB0_2527
	s_mov_b64 s[26:27], 0
	s_mov_b64 s[24:25], -1

.LBB0_2539:
	s_and_b32 s22, s13, 0xff
	s_cmp_lg_u32 s22, 0
	s_mov_b64 s[24:25], -1
	s_nop 0
	s_cbranch_scc1 .LBB0_2542
	global_load_dword v1, v0, s[14:15] sc1
	s_waitcnt vmcnt(0)
	v_cmp_eq_u32_e32 vcc, 0, v1
	s_cbranch_vccnz .LBB0_2544
	s_mov_b64 s[24:25], 0
	s_mov_b64 s[22:23], -1

.LBB0_2591:
	global_load_dword v15, v16, s[4:5] sc1
	s_waitcnt lgkmcnt(0)
	global_load_dword v0, v16, s[6:7] sc1
	global_load_dword v1, v16, s[8:9] sc1
	global_load_dword v2, v16, s[10:11] sc1
	global_load_dword v3, v16, s[14:15] sc1
	global_load_dword v4, v16, s[16:17] sc1
	global_load_dword v5, v16, s[18:19] sc1
	global_load_dword v6, v16, s[20:21] sc1
	global_load_dword v7, v16, s[22:23] sc1
	global_load_dword v8, v16, s[24:25] sc1
	global_load_dword v9, v16, s[26:27] sc1
	global_load_dword v10, v16, s[28:29] sc1
	global_load_dword v11, v16, s[34:35] sc1
	global_load_dword v12, v16, s[36:37] sc1
	global_load_dword v13, v16, s[38:39] sc1
	global_load_dword v14, v16, s[40:41] sc1
	s_mov_b64 s[42:43], -1
	s_mov_b64 s[44:45], -1
	s_waitcnt vmcnt(14)
	v_add_u32_e32 v17, v0, v15
	s_waitcnt vmcnt(13)
	v_add_u32_e32 v17, v17, v1
	s_waitcnt vmcnt(12)
	v_add_u32_e32 v17, v17, v2
	s_waitcnt vmcnt(11)
	v_add_u32_e32 v17, v17, v3
	s_waitcnt vmcnt(10)
	v_add_u32_e32 v17, v17, v4
	s_waitcnt vmcnt(9)
	v_add_u32_e32 v17, v17, v5
	s_waitcnt vmcnt(8)
	v_add_u32_e32 v17, v17, v6
	s_waitcnt vmcnt(7)
	v_add_u32_e32 v17, v17, v7
	s_waitcnt vmcnt(6)
	v_add_u32_e32 v17, v17, v8
	s_waitcnt vmcnt(5)
	v_add_u32_e32 v17, v17, v9
	s_waitcnt vmcnt(4)
	v_add_u32_e32 v17, v17, v10
	s_waitcnt vmcnt(3)
	v_add_u32_e32 v17, v17, v11
	s_waitcnt vmcnt(2)
	v_add_u32_e32 v17, v17, v12
	s_waitcnt vmcnt(1)
	v_add_u32_e32 v17, v17, v13
	s_waitcnt vmcnt(0)
	v_add_u32_e32 v17, v17, v14
	v_cmp_eq_u32_e32 vcc, s13, v17
	s_cbranch_vccnz .LBB0_2590
	s_and_b32 s31, s30, 0xff
	s_cmp_eq_u32 s31, 0
	s_mov_b64 s[46:47], -1
	s_nop 0
	s_cbranch_scc0 .LBB0_2595
	global_load_dword v17, v16, s[2:3] sc1
	s_waitcnt vmcnt(0)
	v_cmp_eq_u32_e32 vcc, 0, v17
	s_cbranch_vccnz .LBB0_2597
	s_mov_b64 s[46:47], 0

.LBB0_2609:
	s_and_b32 s20, s13, 0xff
	s_mov_b64 s[18:19], -1
	s_cmp_lg_u32 s20, 0
	s_mov_b64 s[22:23], -1
	s_nop 0
	s_cbranch_scc1 .LBB0_2612
	global_load_dword v2, v0, s[8:9] sc1
	s_waitcnt vmcnt(0)
	v_cmp_eq_u32_e32 vcc, 0, v2
	s_cbranch_vccnz .LBB0_2614
	s_mov_b64 s[22:23], 0
	s_mov_b64 s[20:21], -1

.LBB0_2626:
	s_and_b32 s18, s13, 0xff
	s_cmp_lg_u32 s18, 0
	s_mov_b64 s[20:21], -1
	s_nop 0
	s_cbranch_scc1 .LBB0_2629
	global_load_dword v1, v0, s[8:9] sc1
	s_waitcnt vmcnt(0)
	v_cmp_eq_u32_e32 vcc, 0, v1
	s_cbranch_vccnz .LBB0_2631
	s_mov_b64 s[20:21], 0
	s_mov_b64 s[18:19], -1
